# speedup vs baseline: 1.0184x; 1.0009x over previous
; __device__ __forceinline__ unsigned cvt_pk_bf16(float lo, float hi) { unsigned r; asm volatile("v_cvt_pk_bf16_f32 %0, %1, %2" : "=v"(r) : "v"(lo), "v"(hi)); return r; }
;     __device__ __forceinline__ void operator()(const f32x4 (&acc)[2][2][4][2], const Unit& u, int wr, int wc, int fr, int fq) const {
;     ...
;                 for (int bj = 0; bj < 2; ++bj) {
;                     const u32x4 hv = hold[ai][m][bj];
;                     f32x4 h0 = {__uint_as_float(hv.x << 16), __uint_as_float(hv.x & 0xffff0000u), __uint_as_float(hv.y << 16), __uint_as_float(hv.y & 0xffff0000u)};
;                     f32x4 h1 = {__uint_as_float(hv.z << 16), __uint_as_float(hv.z & 0xffff0000u), __uint_as_float(hv.w << 16), __uint_as_float(hv.w & 0xffff0000u)};
;                     h0 += acc[ai][bj][m][0]; h1 += acc[ai][bj][m][1];
;                     const int col0 = c0 + bj * HALF;
;                     u32x4 w; w.x = cvt_pk_bf16(h0[0], h0[1]); w.y = cvt_pk_bf16(h0[2], h0[3]); w.z = cvt_pk_bf16(h1[0], h1[1]); w.w = cvt_pk_bf16(h1[2], h1[3]);
;                     if (valid) *(u32x4*)(HB + (size_t)r * 2048 + col0) = w;
;                     h0 = (f32x4){__uint_as_float(w.x << 16), __uint_as_float(w.x & 0xffff0000u), __uint_as_float(w.y << 16), __uint_as_float(w.y & 0xffff0000u)};
;                     h1 = (f32x4){__uint_as_float(w.z << 16), __uint_as_float(w.z & 0xffff0000u), __uint_as_float(w.w << 16), __uint_as_float(w.w & 0xffff0000u)};
; #pragma unroll
;                     for (int j = 0; j < 4; ++j) ssum += h0[j] * h0[j] + h1[j] * h1[j];
;                 }
;                 ssum += __shfl_xor(ssum, 16); ssum += __shfl_xor(ssum, 32);
;                 if (fq == 0 && valid) atomicAdd(ssn + r, (unsigned long long)(ssum * 16777216.f));
.LBB0_212:
	s_or_b64 exec, exec, s[8:9]
	v_lshlrev_b32_e32 v140, 16, v144
	v_and_b32_e32 v141, 0xffff0000, v144
	v_lshlrev_b32_e32 v144, 16, v146
	v_lshlrev_b32_e32 v142, 16, v145
	v_and_b32_e32 v143, 0xffff0000, v145
	v_and_b32_e32 v145, 0xffff0000, v146
	v_mul_f32_e32 v144, v144, v144
	v_lshlrev_b32_e32 v146, 16, v147
	v_fmac_f32_e32 v144, v140, v140
	v_mul_f32_e32 v140, v145, v145
	v_fmac_f32_e32 v140, v141, v141
	v_mul_f32_e32 v141, v146, v146
	v_and_b32_e32 v147, 0xffff0000, v147
	v_add_f32_e32 v140, v144, v140
	v_fmac_f32_e32 v141, v142, v142
	v_add_f32_e32 v140, v140, v141
	v_mul_f32_e32 v141, v147, v147
	v_fmac_f32_e32 v141, v143, v143
	v_lshlrev_b32_e32 v143, 16, v138
	v_add_f32_e32 v140, v141, v140
	v_lshlrev_b32_e32 v141, 16, v136
	v_and_b32_e32 v138, 0xffff0000, v138
	v_mul_f32_e32 v143, v143, v143
	v_and_b32_e32 v136, 0xffff0000, v136
	v_fmac_f32_e32 v143, v141, v141
	v_mul_f32_e32 v138, v138, v138
	v_lshlrev_b32_e32 v144, 16, v139
	v_add_f32_e32 v140, v140, v143
	v_fmac_f32_e32 v138, v136, v136
	v_lshlrev_b32_e32 v142, 16, v137
	v_add_f32_e32 v136, v138, v140
	v_mul_f32_e32 v138, v144, v144
	v_and_b32_e32 v139, 0xffff0000, v139
	v_fmac_f32_e32 v138, v142, v142
	v_and_b32_e32 v137, 0xffff0000, v137
	v_add_f32_e32 v136, v138, v136
	v_mul_f32_e32 v138, v139, v139
	v_fmac_f32_e32 v138, v137, v137
	v_add_f32_e32 v136, v138, v136
	v_and_b32_e32 v138, 64, v232
	v_xor_b32_e32 v137, 16, v232
	v_add_u32_e32 v139, 64, v138
	v_cmp_lt_i32_e64 s[8:9], v137, v139
	s_and_b64 s[36:37], s[4:5], vcc
	s_nop 0
	v_cndmask_b32_e64 v137, v232, v137, s[8:9]
	v_lshlrev_b32_e32 v138, 2, v137
	v_mov_b32_e32 v137, v136
	s_nop 1
	v_permlane16_swap_b32_e32 v137, v136
	v_add_f32_e32 v140, v136, v137
	v_xor_b32_e32 v136, 32, v232
	v_cmp_lt_i32_e64 s[8:9], v136, v139
	s_nop 1
	v_cndmask_b32_e64 v136, v232, v136, s[8:9]
	v_lshlrev_b32_e32 v139, 2, v136
	v_mov_b32_e32 v141, v140
	s_nop 1
	v_permlane32_swap_b32_e32 v141, v140
	v_lshl_add_u64 v[136:137], v[202:203], 3, s[12:13]
	s_and_saveexec_b64 s[8:9], s[36:37]
	s_cbranch_execz .LBB0_214
	s_waitcnt lgkmcnt(0)
	v_add_f32_e32 v140, v140, v141
	v_mul_f32_e32 v140, 0x4b800000, v140
	v_trunc_f32_e32 v140, v140
	v_mul_f32_e32 v141, 0x2f800000, v140
	v_floor_f32_e32 v141, v141
	v_fmac_f32_e32 v140, 0xcf800000, v141
	v_cvt_u32_f32_e32 v140, v140
	v_cvt_u32_f32_e32 v141, v141
	global_atomic_add_x2 v[136:137], v[140:141], off

;     __device__ __forceinline__ void operator()(const f32x4 (&acc)[2][2][4][2], const Unit& u, int wr, int wc, int fr, int fq) const {
;     ...
;                     h0 = (f32x4){__uint_as_float(w.x << 16), __uint_as_float(w.x & 0xffff0000u), __uint_as_float(w.y << 16), __uint_as_float(w.y & 0xffff0000u)};
;                     h1 = (f32x4){__uint_as_float(w.z << 16), __uint_as_float(w.z & 0xffff0000u), __uint_as_float(w.w << 16), __uint_as_float(w.w & 0xffff0000u)};
; #pragma unroll
;                     for (int j = 0; j < 4; ++j) ssum += h0[j] * h0[j] + h1[j] * h1[j];
;                 }
;                 ssum += __shfl_xor(ssum, 16); ssum += __shfl_xor(ssum, 32);
;                 if (fq == 0 && valid) atomicAdd(ssn + r, (unsigned long long)(ssum * 16777216.f));
.LBB0_218:
	s_or_b64 exec, exec, s[8:9]
	v_lshlrev_b32_e32 v116, 16, v120
	v_and_b32_e32 v117, 0xffff0000, v120
	v_lshlrev_b32_e32 v120, 16, v122
	v_lshlrev_b32_e32 v118, 16, v121
	v_and_b32_e32 v119, 0xffff0000, v121
	v_and_b32_e32 v121, 0xffff0000, v122
	v_mul_f32_e32 v120, v120, v120
	v_lshlrev_b32_e32 v122, 16, v123
	v_fmac_f32_e32 v120, v116, v116
	v_mul_f32_e32 v116, v121, v121
	v_fmac_f32_e32 v116, v117, v117
	v_mul_f32_e32 v117, v122, v122
	v_and_b32_e32 v123, 0xffff0000, v123
	v_add_f32_e32 v116, v120, v116
	v_fmac_f32_e32 v117, v118, v118
	v_add_f32_e32 v116, v116, v117
	v_mul_f32_e32 v117, v123, v123
	v_fmac_f32_e32 v117, v119, v119
	v_lshlrev_b32_e32 v119, 16, v114
	v_add_f32_e32 v116, v117, v116
	v_lshlrev_b32_e32 v117, 16, v112
	v_and_b32_e32 v114, 0xffff0000, v114
	v_mul_f32_e32 v119, v119, v119
	v_and_b32_e32 v112, 0xffff0000, v112
	v_fmac_f32_e32 v119, v117, v117
	v_mul_f32_e32 v114, v114, v114
	v_lshlrev_b32_e32 v120, 16, v115
	v_add_f32_e32 v116, v116, v119
	v_fmac_f32_e32 v114, v112, v112
	v_lshlrev_b32_e32 v118, 16, v113
	v_add_f32_e32 v112, v114, v116
	v_mul_f32_e32 v114, v120, v120
	v_and_b32_e32 v115, 0xffff0000, v115
	v_fmac_f32_e32 v114, v118, v118
	v_and_b32_e32 v113, 0xffff0000, v113
	v_add_f32_e32 v112, v114, v112
	v_mul_f32_e32 v114, v115, v115
	v_fmac_f32_e32 v114, v113, v113
	v_add_f32_e32 v112, v114, v112
	v_mov_b32_e32 v113, v112
	s_nop 1
	v_permlane16_swap_b32_e32 v113, v112
	s_and_b64 s[36:37], s[4:5], vcc
	v_add_f32_e32 v112, v112, v113
	v_mov_b32_e32 v113, v112
	s_nop 1
	v_permlane32_swap_b32_e32 v113, v112
	s_and_saveexec_b64 s[8:9], s[36:37]
	s_cbranch_execz .LBB0_220
	s_waitcnt lgkmcnt(0)
	v_add_f32_e32 v112, v112, v113
	v_mul_f32_e32 v112, 0x4b800000, v112
	v_trunc_f32_e32 v112, v112
	v_mul_f32_e32 v113, 0x2f800000, v112
	v_floor_f32_e32 v113, v113
	v_fmac_f32_e32 v112, 0xcf800000, v113
	v_cvt_u32_f32_e32 v112, v112
	v_cvt_u32_f32_e32 v113, v113
	global_atomic_add_x2 v[136:137], v[112:113], off offset:128

;     __device__ __forceinline__ void operator()(const f32x4 (&acc)[2][2][4][2], const Unit& u, int wr, int wc, int fr, int fq) const {
;     ...
;                     h0 = (f32x4){__uint_as_float(w.x << 16), __uint_as_float(w.x & 0xffff0000u), __uint_as_float(w.y << 16), __uint_as_float(w.y & 0xffff0000u)};
;                     h1 = (f32x4){__uint_as_float(w.z << 16), __uint_as_float(w.z & 0xffff0000u), __uint_as_float(w.w << 16), __uint_as_float(w.w & 0xffff0000u)};
; #pragma unroll
;                     for (int j = 0; j < 4; ++j) ssum += h0[j] * h0[j] + h1[j] * h1[j];
;                 }
;                 ssum += __shfl_xor(ssum, 16); ssum += __shfl_xor(ssum, 32);
;                 if (fq == 0 && valid) atomicAdd(ssn + r, (unsigned long long)(ssum * 16777216.f));
.LBB0_224:
	s_or_b64 exec, exec, s[8:9]
	v_lshlrev_b32_e32 v92, 16, v96
	v_and_b32_e32 v93, 0xffff0000, v96
	v_lshlrev_b32_e32 v96, 16, v98
	v_lshlrev_b32_e32 v94, 16, v97
	v_and_b32_e32 v95, 0xffff0000, v97
	v_and_b32_e32 v97, 0xffff0000, v98
	v_mul_f32_e32 v96, v96, v96
	v_lshlrev_b32_e32 v98, 16, v99
	v_fmac_f32_e32 v96, v92, v92
	v_mul_f32_e32 v92, v97, v97
	v_fmac_f32_e32 v92, v93, v93
	v_mul_f32_e32 v93, v98, v98
	v_and_b32_e32 v99, 0xffff0000, v99
	v_add_f32_e32 v92, v96, v92
	v_fmac_f32_e32 v93, v94, v94
	v_add_f32_e32 v92, v92, v93
	v_mul_f32_e32 v93, v99, v99
	v_fmac_f32_e32 v93, v95, v95
	v_lshlrev_b32_e32 v95, 16, v86
	v_add_f32_e32 v92, v93, v92
	v_lshlrev_b32_e32 v93, 16, v84
	v_and_b32_e32 v86, 0xffff0000, v86
	v_mul_f32_e32 v95, v95, v95
	v_and_b32_e32 v84, 0xffff0000, v84
	v_fmac_f32_e32 v95, v93, v93
	v_mul_f32_e32 v86, v86, v86
	v_lshlrev_b32_e32 v96, 16, v87
	v_add_f32_e32 v92, v92, v95
	v_fmac_f32_e32 v86, v84, v84
	v_lshlrev_b32_e32 v94, 16, v85
	v_add_f32_e32 v84, v86, v92
	v_mul_f32_e32 v86, v96, v96
	v_and_b32_e32 v87, 0xffff0000, v87
	v_fmac_f32_e32 v86, v94, v94
	v_and_b32_e32 v85, 0xffff0000, v85
	v_add_f32_e32 v84, v86, v84
	v_mul_f32_e32 v86, v87, v87
	v_fmac_f32_e32 v86, v85, v85
	v_add_f32_e32 v84, v86, v84
	v_mov_b32_e32 v85, v84
	s_nop 1
	v_permlane16_swap_b32_e32 v85, v84
	s_and_b64 s[36:37], s[4:5], vcc
	v_add_f32_e32 v84, v84, v85
	v_mov_b32_e32 v85, v84
	s_nop 1
	v_permlane32_swap_b32_e32 v85, v84
	s_and_saveexec_b64 s[8:9], s[36:37]
	s_cbranch_execz .LBB0_226
	s_waitcnt lgkmcnt(0)
	v_add_f32_e32 v84, v84, v85
	v_mul_f32_e32 v84, 0x4b800000, v84
	v_trunc_f32_e32 v84, v84
	v_mul_f32_e32 v85, 0x2f800000, v84
	v_floor_f32_e32 v85, v85
	v_fmac_f32_e32 v84, 0xcf800000, v85
	v_cvt_u32_f32_e32 v84, v84
	v_cvt_u32_f32_e32 v85, v85
	global_atomic_add_x2 v[136:137], v[84:85], off offset:256

;     __device__ __forceinline__ void operator()(const f32x4 (&acc)[2][2][4][2], const Unit& u, int wr, int wc, int fr, int fq) const {
;     ...
;                     h0 = (f32x4){__uint_as_float(w.x << 16), __uint_as_float(w.x & 0xffff0000u), __uint_as_float(w.y << 16), __uint_as_float(w.y & 0xffff0000u)};
;                     h1 = (f32x4){__uint_as_float(w.z << 16), __uint_as_float(w.z & 0xffff0000u), __uint_as_float(w.w << 16), __uint_as_float(w.w & 0xffff0000u)};
; #pragma unroll
;                     for (int j = 0; j < 4; ++j) ssum += h0[j] * h0[j] + h1[j] * h1[j];
;                 }
;                 ssum += __shfl_xor(ssum, 16); ssum += __shfl_xor(ssum, 32);
;                 if (fq == 0 && valid) atomicAdd(ssn + r, (unsigned long long)(ssum * 16777216.f));
.LBB0_230:
	s_or_b64 exec, exec, s[8:9]
	v_lshlrev_b32_e32 v68, 16, v72
	v_and_b32_e32 v69, 0xffff0000, v72
	v_lshlrev_b32_e32 v72, 16, v74
	v_lshlrev_b32_e32 v70, 16, v73
	v_and_b32_e32 v71, 0xffff0000, v73
	v_and_b32_e32 v73, 0xffff0000, v74
	v_mul_f32_e32 v72, v72, v72
	v_lshlrev_b32_e32 v74, 16, v75
	v_fmac_f32_e32 v72, v68, v68
	v_mul_f32_e32 v68, v73, v73
	v_fmac_f32_e32 v68, v69, v69
	v_mul_f32_e32 v69, v74, v74
	v_and_b32_e32 v75, 0xffff0000, v75
	v_add_f32_e32 v68, v72, v68
	v_fmac_f32_e32 v69, v70, v70
	v_add_f32_e32 v68, v68, v69
	v_mul_f32_e32 v69, v75, v75
	v_fmac_f32_e32 v69, v71, v71
	v_lshlrev_b32_e32 v71, 16, v66
	v_add_f32_e32 v68, v69, v68
	v_lshlrev_b32_e32 v69, 16, v64
	v_and_b32_e32 v66, 0xffff0000, v66
	v_mul_f32_e32 v71, v71, v71
	v_and_b32_e32 v64, 0xffff0000, v64
	v_fmac_f32_e32 v71, v69, v69
	v_mul_f32_e32 v66, v66, v66
	v_lshlrev_b32_e32 v72, 16, v67
	v_add_f32_e32 v68, v68, v71
	v_fmac_f32_e32 v66, v64, v64
	v_lshlrev_b32_e32 v70, 16, v65
	v_add_f32_e32 v64, v66, v68
	v_mul_f32_e32 v66, v72, v72
	v_and_b32_e32 v67, 0xffff0000, v67
	v_fmac_f32_e32 v66, v70, v70
	v_and_b32_e32 v65, 0xffff0000, v65
	v_add_f32_e32 v64, v66, v64
	v_mul_f32_e32 v66, v67, v67
	v_fmac_f32_e32 v66, v65, v65
	v_add_f32_e32 v64, v66, v64
	v_mov_b32_e32 v65, v64
	s_nop 1
	v_permlane16_swap_b32_e32 v65, v64
	s_and_b64 s[36:37], s[4:5], vcc
	v_add_f32_e32 v64, v64, v65
	v_mov_b32_e32 v65, v64
	s_nop 1
	v_permlane32_swap_b32_e32 v65, v64
	s_and_saveexec_b64 s[8:9], s[36:37]
	s_cbranch_execz .LBB0_232
	s_waitcnt lgkmcnt(0)
	v_add_f32_e32 v64, v64, v65
	v_mul_f32_e32 v64, 0x4b800000, v64
	v_trunc_f32_e32 v64, v64
	v_mul_f32_e32 v65, 0x2f800000, v64
	v_floor_f32_e32 v65, v65
	v_fmac_f32_e32 v64, 0xcf800000, v65
	v_cvt_u32_f32_e32 v64, v64
	v_cvt_u32_f32_e32 v65, v65
	global_atomic_add_x2 v[136:137], v[64:65], off offset:384

;     __device__ __forceinline__ void operator()(const f32x4 (&acc)[2][2][4][2], const Unit& u, int wr, int wc, int fr, int fq) const {
;     ...
;                     h0 = (f32x4){__uint_as_float(w.x << 16), __uint_as_float(w.x & 0xffff0000u), __uint_as_float(w.y << 16), __uint_as_float(w.y & 0xffff0000u)};
;                     h1 = (f32x4){__uint_as_float(w.z << 16), __uint_as_float(w.z & 0xffff0000u), __uint_as_float(w.w << 16), __uint_as_float(w.w & 0xffff0000u)};
; #pragma unroll
;                     for (int j = 0; j < 4; ++j) ssum += h0[j] * h0[j] + h1[j] * h1[j];
;                 }
;                 ssum += __shfl_xor(ssum, 16); ssum += __shfl_xor(ssum, 32);
;                 if (fq == 0 && valid) atomicAdd(ssn + r, (unsigned long long)(ssum * 16777216.f));
.LBB0_236:
	s_or_b64 exec, exec, s[8:9]
	v_lshlrev_b32_e32 v52, 16, v56
	v_and_b32_e32 v53, 0xffff0000, v56
	v_lshlrev_b32_e32 v56, 16, v58
	v_lshlrev_b32_e32 v54, 16, v57
	v_and_b32_e32 v55, 0xffff0000, v57
	v_and_b32_e32 v57, 0xffff0000, v58
	v_mul_f32_e32 v56, v56, v56
	v_lshlrev_b32_e32 v58, 16, v59
	v_fmac_f32_e32 v56, v52, v52
	v_mul_f32_e32 v52, v57, v57
	v_fmac_f32_e32 v52, v53, v53
	v_mul_f32_e32 v53, v58, v58
	v_and_b32_e32 v59, 0xffff0000, v59
	v_add_f32_e32 v52, v56, v52
	v_fmac_f32_e32 v53, v54, v54
	v_add_f32_e32 v52, v52, v53
	v_mul_f32_e32 v53, v59, v59
	v_fmac_f32_e32 v53, v55, v55
	v_lshlrev_b32_e32 v55, 16, v50
	v_add_f32_e32 v52, v53, v52
	v_lshlrev_b32_e32 v53, 16, v48
	v_and_b32_e32 v50, 0xffff0000, v50
	v_mul_f32_e32 v55, v55, v55
	v_and_b32_e32 v48, 0xffff0000, v48
	v_fmac_f32_e32 v55, v53, v53
	v_mul_f32_e32 v50, v50, v50
	v_lshlrev_b32_e32 v56, 16, v51
	v_add_f32_e32 v52, v52, v55
	v_fmac_f32_e32 v50, v48, v48
	v_lshlrev_b32_e32 v54, 16, v49
	v_add_f32_e32 v48, v50, v52
	v_mul_f32_e32 v50, v56, v56
	v_and_b32_e32 v51, 0xffff0000, v51
	v_fmac_f32_e32 v50, v54, v54
	v_and_b32_e32 v49, 0xffff0000, v49
	v_add_f32_e32 v48, v50, v48
	v_mul_f32_e32 v50, v51, v51
	v_fmac_f32_e32 v50, v49, v49
	v_add_f32_e32 v48, v50, v48
	v_mov_b32_e32 v49, v48
	s_nop 1
	v_permlane16_swap_b32_e32 v49, v48
	s_and_b64 s[36:37], s[4:5], vcc
	v_add_f32_e32 v48, v48, v49
	v_mov_b32_e32 v49, v48
	s_nop 1
	v_permlane32_swap_b32_e32 v49, v48
	s_and_saveexec_b64 s[8:9], s[36:37]
	s_cbranch_execz .LBB0_238
	s_waitcnt lgkmcnt(0)
	v_add_f32_e32 v48, v48, v49
	v_mul_f32_e32 v48, 0x4b800000, v48
	v_trunc_f32_e32 v48, v48
	v_mul_f32_e32 v49, 0x2f800000, v48
	v_floor_f32_e32 v49, v49
	v_fmac_f32_e32 v48, 0xcf800000, v49
	v_cvt_u32_f32_e32 v48, v48
	v_cvt_u32_f32_e32 v49, v49
	global_atomic_add_x2 v[136:137], v[48:49], off offset:1024

;     __device__ __forceinline__ void operator()(const f32x4 (&acc)[2][2][4][2], const Unit& u, int wr, int wc, int fr, int fq) const {
;     ...
;                     h0 = (f32x4){__uint_as_float(w.x << 16), __uint_as_float(w.x & 0xffff0000u), __uint_as_float(w.y << 16), __uint_as_float(w.y & 0xffff0000u)};
;                     h1 = (f32x4){__uint_as_float(w.z << 16), __uint_as_float(w.z & 0xffff0000u), __uint_as_float(w.w << 16), __uint_as_float(w.w & 0xffff0000u)};
; #pragma unroll
;                     for (int j = 0; j < 4; ++j) ssum += h0[j] * h0[j] + h1[j] * h1[j];
;                 }
;                 ssum += __shfl_xor(ssum, 16); ssum += __shfl_xor(ssum, 32);
;                 if (fq == 0 && valid) atomicAdd(ssn + r, (unsigned long long)(ssum * 16777216.f));
.LBB0_242:
	s_or_b64 exec, exec, s[8:9]
	v_lshlrev_b32_e32 v36, 16, v40
	v_and_b32_e32 v37, 0xffff0000, v40
	v_lshlrev_b32_e32 v40, 16, v42
	v_lshlrev_b32_e32 v38, 16, v41
	v_and_b32_e32 v39, 0xffff0000, v41
	v_and_b32_e32 v41, 0xffff0000, v42
	v_mul_f32_e32 v40, v40, v40
	v_lshlrev_b32_e32 v42, 16, v43
	v_fmac_f32_e32 v40, v36, v36
	v_mul_f32_e32 v36, v41, v41
	v_fmac_f32_e32 v36, v37, v37
	v_mul_f32_e32 v37, v42, v42
	v_and_b32_e32 v43, 0xffff0000, v43
	v_add_f32_e32 v36, v40, v36
	v_fmac_f32_e32 v37, v38, v38
	v_add_f32_e32 v36, v36, v37
	v_mul_f32_e32 v37, v43, v43
	v_fmac_f32_e32 v37, v39, v39
	v_lshlrev_b32_e32 v39, 16, v34
	v_add_f32_e32 v36, v37, v36
	v_lshlrev_b32_e32 v37, 16, v32
	v_and_b32_e32 v34, 0xffff0000, v34
	v_mul_f32_e32 v39, v39, v39
	v_and_b32_e32 v32, 0xffff0000, v32
	v_fmac_f32_e32 v39, v37, v37
	v_mul_f32_e32 v34, v34, v34
	v_lshlrev_b32_e32 v40, 16, v35
	v_add_f32_e32 v36, v36, v39
	v_fmac_f32_e32 v34, v32, v32
	v_lshlrev_b32_e32 v38, 16, v33
	v_add_f32_e32 v32, v34, v36
	v_mul_f32_e32 v34, v40, v40
	v_and_b32_e32 v35, 0xffff0000, v35
	v_fmac_f32_e32 v34, v38, v38
	v_and_b32_e32 v33, 0xffff0000, v33
	v_add_f32_e32 v32, v34, v32
	v_mul_f32_e32 v34, v35, v35
	v_fmac_f32_e32 v34, v33, v33
	v_add_f32_e32 v32, v34, v32
	v_mov_b32_e32 v33, v32
	s_nop 1
	v_permlane16_swap_b32_e32 v33, v32
	s_and_b64 s[36:37], s[4:5], vcc
	v_add_f32_e32 v32, v32, v33
	v_mov_b32_e32 v33, v32
	s_nop 1
	v_permlane32_swap_b32_e32 v33, v32
	s_and_saveexec_b64 s[8:9], s[36:37]
	s_cbranch_execz .LBB0_244
	s_waitcnt lgkmcnt(0)
	v_add_f32_e32 v32, v32, v33
	v_mul_f32_e32 v32, 0x4b800000, v32
	v_trunc_f32_e32 v32, v32
	v_mul_f32_e32 v33, 0x2f800000, v32
	v_floor_f32_e32 v33, v33
	v_fmac_f32_e32 v32, 0xcf800000, v33
	v_cvt_u32_f32_e32 v32, v32
	v_cvt_u32_f32_e32 v33, v33
	global_atomic_add_x2 v[136:137], v[32:33], off offset:1152

;     __device__ __forceinline__ void operator()(const f32x4 (&acc)[2][2][4][2], const Unit& u, int wr, int wc, int fr, int fq) const {
;     ...
;                     h0 = (f32x4){__uint_as_float(w.x << 16), __uint_as_float(w.x & 0xffff0000u), __uint_as_float(w.y << 16), __uint_as_float(w.y & 0xffff0000u)};
;                     h1 = (f32x4){__uint_as_float(w.z << 16), __uint_as_float(w.z & 0xffff0000u), __uint_as_float(w.w << 16), __uint_as_float(w.w & 0xffff0000u)};
; #pragma unroll
;                     for (int j = 0; j < 4; ++j) ssum += h0[j] * h0[j] + h1[j] * h1[j];
;                 }
;                 ssum += __shfl_xor(ssum, 16); ssum += __shfl_xor(ssum, 32);
;                 if (fq == 0 && valid) atomicAdd(ssn + r, (unsigned long long)(ssum * 16777216.f));
.LBB0_248:
	s_or_b64 exec, exec, s[8:9]
	v_lshlrev_b32_e32 v20, 16, v24
	v_and_b32_e32 v21, 0xffff0000, v24
	v_lshlrev_b32_e32 v24, 16, v26
	v_lshlrev_b32_e32 v22, 16, v25
	v_and_b32_e32 v23, 0xffff0000, v25
	v_and_b32_e32 v25, 0xffff0000, v26
	v_mul_f32_e32 v24, v24, v24
	v_lshlrev_b32_e32 v26, 16, v27
	v_fmac_f32_e32 v24, v20, v20
	v_mul_f32_e32 v20, v25, v25
	v_fmac_f32_e32 v20, v21, v21
	v_mul_f32_e32 v21, v26, v26
	v_and_b32_e32 v27, 0xffff0000, v27
	v_add_f32_e32 v20, v24, v20
	v_fmac_f32_e32 v21, v22, v22
	v_add_f32_e32 v20, v20, v21
	v_mul_f32_e32 v21, v27, v27
	v_fmac_f32_e32 v21, v23, v23
	v_lshlrev_b32_e32 v23, 16, v18
	v_add_f32_e32 v20, v21, v20
	v_lshlrev_b32_e32 v21, 16, v16
	v_and_b32_e32 v18, 0xffff0000, v18
	v_mul_f32_e32 v23, v23, v23
	v_and_b32_e32 v16, 0xffff0000, v16
	v_fmac_f32_e32 v23, v21, v21
	v_mul_f32_e32 v18, v18, v18
	v_lshlrev_b32_e32 v24, 16, v19
	v_add_f32_e32 v20, v20, v23
	v_fmac_f32_e32 v18, v16, v16
	v_lshlrev_b32_e32 v22, 16, v17
	v_add_f32_e32 v16, v18, v20
	v_mul_f32_e32 v18, v24, v24
	v_and_b32_e32 v19, 0xffff0000, v19
	v_fmac_f32_e32 v18, v22, v22
	v_and_b32_e32 v17, 0xffff0000, v17
	v_add_f32_e32 v16, v18, v16
	v_mul_f32_e32 v18, v19, v19
	v_fmac_f32_e32 v18, v17, v17
	v_add_f32_e32 v16, v18, v16
	v_mov_b32_e32 v17, v16
	s_nop 1
	v_permlane16_swap_b32_e32 v17, v16
	s_and_b64 s[36:37], s[4:5], vcc
	v_add_f32_e32 v16, v16, v17
	v_mov_b32_e32 v17, v16
	s_nop 1
	v_permlane32_swap_b32_e32 v17, v16
	s_and_saveexec_b64 s[8:9], s[36:37]
	s_cbranch_execz .LBB0_250
	s_waitcnt lgkmcnt(0)
	v_add_f32_e32 v16, v16, v17
	v_mul_f32_e32 v16, 0x4b800000, v16
	v_trunc_f32_e32 v16, v16
	v_mul_f32_e32 v17, 0x2f800000, v16
	v_floor_f32_e32 v17, v17
	v_fmac_f32_e32 v16, 0xcf800000, v17
	v_cvt_u32_f32_e32 v16, v16
	v_cvt_u32_f32_e32 v17, v17
	global_atomic_add_x2 v[136:137], v[16:17], off offset:1280

;     __device__ __forceinline__ void operator()(const f32x4 (&acc)[2][2][4][2], const Unit& u, int wr, int wc, int fr, int fq) const {
;     ...
;                     h0 = (f32x4){__uint_as_float(w.x << 16), __uint_as_float(w.x & 0xffff0000u), __uint_as_float(w.y << 16), __uint_as_float(w.y & 0xffff0000u)};
;                     h1 = (f32x4){__uint_as_float(w.z << 16), __uint_as_float(w.z & 0xffff0000u), __uint_as_float(w.w << 16), __uint_as_float(w.w & 0xffff0000u)};
; #pragma unroll
;                     for (int j = 0; j < 4; ++j) ssum += h0[j] * h0[j] + h1[j] * h1[j];
;                 }
;                 ssum += __shfl_xor(ssum, 16); ssum += __shfl_xor(ssum, 32);
;                 if (fq == 0 && valid) atomicAdd(ssn + r, (unsigned long long)(ssum * 16777216.f));
.LBB0_254:
	s_or_b64 exec, exec, s[8:9]
	v_lshlrev_b32_e32 v4, 16, v8
	v_and_b32_e32 v5, 0xffff0000, v8
	v_lshlrev_b32_e32 v8, 16, v10
	v_lshlrev_b32_e32 v6, 16, v9
	v_and_b32_e32 v7, 0xffff0000, v9
	v_and_b32_e32 v9, 0xffff0000, v10
	v_mul_f32_e32 v8, v8, v8
	v_lshlrev_b32_e32 v10, 16, v11
	v_fmac_f32_e32 v8, v4, v4
	v_mul_f32_e32 v4, v9, v9
	v_fmac_f32_e32 v4, v5, v5
	v_mul_f32_e32 v5, v10, v10
	v_and_b32_e32 v11, 0xffff0000, v11
	v_add_f32_e32 v4, v8, v4
	v_fmac_f32_e32 v5, v6, v6
	v_add_f32_e32 v4, v4, v5
	v_mul_f32_e32 v5, v11, v11
	v_fmac_f32_e32 v5, v7, v7
	v_lshlrev_b32_e32 v7, 16, v2
	v_add_f32_e32 v4, v5, v4
	v_lshlrev_b32_e32 v5, 16, v0
	v_and_b32_e32 v2, 0xffff0000, v2
	v_mul_f32_e32 v7, v7, v7
	v_and_b32_e32 v0, 0xffff0000, v0
	v_fmac_f32_e32 v7, v5, v5
	v_mul_f32_e32 v2, v2, v2
	v_lshlrev_b32_e32 v8, 16, v3
	v_add_f32_e32 v4, v4, v7
	v_fmac_f32_e32 v2, v0, v0
	v_lshlrev_b32_e32 v6, 16, v1
	v_add_f32_e32 v0, v2, v4
	v_mul_f32_e32 v2, v8, v8
	v_and_b32_e32 v3, 0xffff0000, v3
	v_fmac_f32_e32 v2, v6, v6
	v_and_b32_e32 v1, 0xffff0000, v1
	v_add_f32_e32 v0, v2, v0
	v_mul_f32_e32 v2, v3, v3
	v_fmac_f32_e32 v2, v1, v1
	v_add_f32_e32 v0, v2, v0
	v_mov_b32_e32 v1, v0
	s_nop 1
	v_permlane16_swap_b32_e32 v1, v0
	s_and_b64 s[36:37], s[4:5], vcc
	v_add_f32_e32 v0, v0, v1
	v_mov_b32_e32 v1, v0
	s_nop 1
	v_permlane32_swap_b32_e32 v1, v0
	s_and_saveexec_b64 s[8:9], s[36:37]
	s_cbranch_execz .LBB0_256
	s_waitcnt lgkmcnt(0)
	v_add_f32_e32 v0, v0, v1
	v_mul_f32_e32 v0, 0x4b800000, v0
	v_trunc_f32_e32 v0, v0
	v_mul_f32_e32 v1, 0x2f800000, v0
	v_floor_f32_e32 v1, v1
	v_fmac_f32_e32 v0, 0xcf800000, v1
	v_cvt_u32_f32_e32 v0, v0
	v_cvt_u32_f32_e32 v1, v1
	global_atomic_add_x2 v[136:137], v[0:1], off offset:1408
